# GEMM phases (1,6,8,9,11): one static s_setprio 1 for the later-dispatched half of the grid (workgroup id bit 8), reset at the phase barrier
# speedup vs baseline: 1.0199x; 1.0053x over previous
.LBB0_7:
	s_mov_b32 s38, s42
	s_mov_b32 s0, 0xb42
	s_bitcmp1_b32 s0, s42
	s_cbranch_scc0 .Lgemm_np
	s_bitcmp1_b32 s50, 8
	s_cbranch_scc0 .Lgemm_np
	s_setprio 1
.Lgemm_np:
	s_cmp_lt_i32 s38, 6
	s_mov_b64 s[0:1], -1
	s_cbranch_scc1 .LBB0_173
	s_cmp_lt_i32 s38, 9
	s_cbranch_scc1 .LBB0_89
	s_cmp_lt_i32 s38, 11
	s_cbranch_scc1 .LBB0_40
	s_cmp_lt_i32 s38, 12
	s_cbranch_scc1 .LBB0_33
	s_cmp_eq_u32 s38, 12
	s_cbranch_scc0 .LBB0_32
	v_readfirstlane_b32 s2, v184
	v_readfirstlane_b32 s3, v185
	v_mov_b32_e32 v1, v189
	s_nop 0
	v_ashrrev_i32_e32 v0, 6, v1
	v_add_u32_e32 v0, s62, v0
	v_cmp_gt_i32_e32 vcc, s76, v0
	s_and_saveexec_b64 s[0:1], vcc
	s_cbranch_execz .LBB0_31
	v_and_b32_e32 v1, 63, v1
	v_cmp_lt_i32_e32 vcc, v228, v227
	v_lshlrev_b32_e32 v186, 4, v1
	v_lshlrev_b32_e32 v2, 3, v1
	v_cndmask_b32_e32 v1, v226, v228, vcc
	v_cmp_lt_i32_e32 vcc, v229, v227
	v_readlane_b32 s4, v254, 2
	v_mov_b32_e32 v3, v187
	v_lshlrev_b32_e32 v118, 2, v1
	v_cndmask_b32_e32 v1, v226, v229, vcc
	v_cmp_lt_i32_e32 vcc, v230, v227
	v_readlane_b32 s5, v254, 3
	v_lshl_add_u64 v[2:3], s[2:3], 0, v[2:3]
	s_mov_b64 s[2:3], 0x8000000
	s_waitcnt vmcnt(8)
	v_lshlrev_b32_e32 v124, 2, v1
	v_cndmask_b32_e32 v1, v226, v230, vcc
	v_cmp_lt_i32_e32 vcc, v231, v227
	v_lshl_add_u64 v[68:69], s[4:5], 0, v[186:187]
	v_lshl_add_u64 v[70:71], v[2:3], 0, s[2:3]
	v_lshlrev_b32_e32 v126, 2, v1
	v_cndmask_b32_e32 v1, v226, v231, vcc
	v_cmp_lt_i32_e32 vcc, v232, v227
	s_mov_b64 s[2:3], 0x1400
	s_waitcnt vmcnt(3)
	v_lshlrev_b32_e32 v146, 2, v1
	v_cndmask_b32_e32 v1, v226, v232, vcc
	v_cmp_lt_i32_e32 vcc, v233, v227
	v_lshl_add_u64 v[74:75], v[68:69], 0, s[2:3]
	s_mov_b64 s[2:3], 0x1800
	v_readlane_b32 s6, v254, 4
	v_readlane_b32 s7, v254, 5
	s_waitcnt vmcnt(2)
	v_lshlrev_b32_e32 v148, 2, v1
	v_cndmask_b32_e32 v1, v226, v233, vcc
	v_lshl_add_u64 v[76:77], v[68:69], 0, s[2:3]
	s_mov_b64 s[2:3], 0x1c00
	v_lshlrev_b32_e32 v180, 2, v1
	v_lshl_add_u64 v[72:73], v[68:69], 0, s[86:87]
	v_lshl_add_u64 v[78:79], v[68:69], 0, s[2:3]
	v_lshl_add_u64 v[80:81], s[6:7], 0, v[186:187]
	s_mov_b64 s[2:3], 0
	global_load_dwordx4 v[210:213], v[68:69], off
	global_load_dwordx4 v[214:217], v[68:69], off offset:1024
	global_load_dwordx4 v[218:221], v[68:69], off offset:2048
	global_load_dwordx4 v[222:225], v[68:69], off offset:3072
	global_load_dwordx4 v[234:237], v[72:73], off
	global_load_dwordx4 v[238:241], v[74:75], off
	global_load_dwordx4 v[242:245], v[76:77], off
	global_load_dwordx4 v[246:249], v[78:79], off
	s_branch .LBB0_15

.LBB0_539:
	s_setprio 0
	s_cmp_eq_u32 s42, 12
	s_cbranch_scc1 .LBB0_600
	s_and_saveexec_b64 s[0:1], s[96:97]
	s_cbranch_execz .LBB0_551
	v_readlane_b32 s2, v254, 36
	v_readlane_b32 s3, v254, 37
	s_waitcnt lgkmcnt(0)
	s_barrier
	s_and_b64 exec, exec, s[2:3]
	s_cbranch_execz .LBB0_550
	buffer_wbl2 sc1
	s_waitcnt vmcnt(0)
	s_load_dwordx2 s[2:3], s[60:61], 0x58
	s_mov_b64 s[4:5], exec
	v_mbcnt_lo_u32_b32 v1, s4, 0
	v_mbcnt_hi_u32_b32 v1, s5, v1
	v_cmp_eq_u32_e32 vcc, 0, v1
	s_waitcnt lgkmcnt(0)
	global_load_dword v0, v187, s[2:3] offset:40
	s_and_saveexec_b64 s[6:7], vcc
	s_cbranch_execz .LBB0_543
	s_bcnt1_i32_b64 s4, s[4:5]
	v_mov_b32_e32 v2, s4
	global_atomic_add v2, v187, v2, s[2:3] offset:32 sc0
